# LN loop A: per-row fma reads the hoisted modulation registers directly, 16 per-row v_mov_b64 copies removed (on top of the sample-row spreading)
# speedup vs baseline: 1.0075x; 1.0075x over previous
.LBB0_1220:
	s_waitcnt vmcnt(7)
	s_add_i32 s3, s3, 1
	s_addk_i32 s10, 0x100
	v_mov_b64_e32 v[110:111], v[62:63]
	v_mov_b64_e32 v[106:107], v[58:59]
	v_mov_b64_e32 v[102:103], v[54:55]
	v_mov_b64_e32 v[90:91], v[50:51]
	v_pk_fma_f32 v[64:65], v[226:227], v[74:75], v[216:217]
	s_cmp_lg_u32 s11, s3
	v_mov_b64_e32 v[108:109], v[60:61]
	v_mov_b64_e32 v[104:105], v[56:57]
	v_mov_b64_e32 v[100:101], v[52:53]
	v_mov_b64_e32 v[88:89], v[48:49]
	v_pk_fma_f32 v[66:67], v[228:229], v[72:73], v[218:219]
	v_cvt_pk_bf16_f32 v64, v64, v65
	s_nop 0
	v_cvt_pk_bf16_f32 v65, v66, v67
	global_store_dwordx2 v[92:93], v[64:65], off offset:1536
	s_cbranch_scc0 .LBB0_1235

.Lmy_lnh_a_copy:
	s_waitcnt vmcnt(4)
	v_mov_b64_e32 v[50:51], v[46:47]
	v_mov_b64_e32 v[54:55], v[42:43]
	v_mov_b64_e32 v[58:59], v[34:35]
	s_add_i32 s8, s3, 2
	v_mov_b64_e32 v[62:63], v[38:39]
	v_mov_b64_e32 v[48:49], v[44:45]
	v_mov_b64_e32 v[52:53], v[40:41]
	v_mov_b64_e32 v[56:57], v[32:33]
	s_cmp_ge_u32 s8, s11
	v_mov_b64_e32 v[60:61], v[36:37]
	s_cbranch_scc1 .Lmy_lnA_noprefetch
	s_add_i32 s8, s10, 0x200
	s_cmp_lt_u32 s3, 6
	s_cselect_b32 s8, s8, s18
	s_ashr_i32 s9, s8, 31
	s_lshl_b64 s[8:9], s[8:9], 12
	v_lshl_add_u64 v[44:45], v[154:155], 0, s[8:9]
	global_load_dwordx4 v[36:39], v[44:45], off
	global_load_dwordx4 v[32:35], v[44:45], off offset:1024
	global_load_dwordx4 v[40:43], v[44:45], off offset:2048
	s_nop 0
	global_load_dwordx4 v[44:47], v[44:45], off offset:3072
	s_branch .LBB0_1223

.LBB0_1229:
	s_waitcnt vmcnt(9)
	s_lshl_b64 s[12:13], s[12:13], 10
	v_pk_fma_f32 v[94:95], v[188:189], v[108:109], v[180:181]
	v_pk_fma_f32 v[92:93], v[186:187], v[112:113], v[178:179]
	v_mov_b32_e32 v114, v104
	v_mov_b32_e32 v115, v110
	v_mov_b32_e32 v107, v106
	v_cvt_pk_bf16_f32 v96, v92, v93
	v_cvt_pk_bf16_f32 v97, v94, v95
	v_lshl_add_u64 v[92:93], s[12:13], 1, v[156:157]
	v_mov_b32_e32 v94, v106
	v_mov_b32_e32 v95, v106
	v_mov_b32_e32 v104, v111
	global_store_dwordx2 v[92:93], v[96:97], off
	v_pk_mul_f32 v[96:97], v[104:105], v[94:95]
	v_pk_mul_f32 v[98:99], v[114:115], v[106:107]
	v_pk_fma_f32 v[96:97], v[6:7], v[96:97], v[14:15]
	s_and_b64 vcc, exec, s[8:9]
	v_pk_fma_f32 v[98:99], v[4:5], v[98:99], v[12:13]
	s_cbranch_vccnz .LBB0_1231
	v_pk_mul_f32 v[110:111], v[96:97], s[58:59] op_sel_hi:[1,0]
	v_pk_mul_f32 v[108:109], v[98:99], s[58:59] op_sel_hi:[1,0]
	global_store_dwordx4 v144, v[108:111], s[16:17] offset:1024
.LBB0_1231:
	s_waitcnt vmcnt(9)
	v_pk_fma_f32 v[80:81], v[190:191], v[98:99], v[182:183]
	v_pk_fma_f32 v[82:83], v[192:193], v[96:97], v[184:185]
	v_cvt_pk_bf16_f32 v80, v80, v81
	s_and_b64 vcc, exec, s[8:9]
	v_cvt_pk_bf16_f32 v81, v82, v83
	global_store_dwordx2 v[92:93], v[80:81], off offset:512
	v_pk_mul_f32 v[80:81], v[102:103], v[94:95]
	v_pk_mul_f32 v[82:83], v[100:101], v[106:107]
	v_pk_fma_f32 v[80:81], v[18:19], v[80:81], v[26:27]
	v_pk_fma_f32 v[82:83], v[16:17], v[82:83], v[24:25]
	s_cbranch_vccnz .LBB0_1233
	v_pk_mul_f32 v[86:87], v[80:81], s[58:59] op_sel_hi:[1,0]
	v_pk_mul_f32 v[84:85], v[82:83], s[58:59] op_sel_hi:[1,0]
	global_store_dwordx4 v144, v[84:87], s[16:17] offset:2048
.LBB0_1233:
	s_waitcnt vmcnt(7)
	v_pk_fma_f32 v[72:73], v[222:223], v[82:83], v[212:213]
	v_pk_fma_f32 v[74:75], v[224:225], v[80:81], v[214:215]
	v_cvt_pk_bf16_f32 v72, v72, v73
	s_and_b64 vcc, exec, s[8:9]
	v_cvt_pk_bf16_f32 v73, v74, v75
	global_store_dwordx2 v[92:93], v[72:73], off offset:1024
	v_mov_b32_e32 v72, v106
	v_mov_b32_e32 v73, v106
	v_pk_mul_f32 v[72:73], v[90:91], v[72:73]
	v_pk_mul_f32 v[74:75], v[88:89], v[106:107]
	v_pk_fma_f32 v[72:73], v[22:23], v[72:73], v[30:31]
	v_pk_fma_f32 v[74:75], v[20:21], v[74:75], v[28:29]
	s_cbranch_vccnz .LBB0_1220
	v_pk_mul_f32 v[78:79], v[72:73], s[58:59] op_sel_hi:[1,0]
	v_pk_mul_f32 v[76:77], v[74:75], s[58:59] op_sel_hi:[1,0]
	global_store_dwordx4 v144, v[76:79], s[16:17] offset:3072
	s_branch .LBB0_1220
